# FoX loop: running reference (sigma) folded into the score MFMAs (one extra MFMA per 32-key sub-tile); per-tile row max, subtraction and alpha removed from steady state; rescale only when a tile row-su
# speedup vs baseline: 1.0535x; 1.0097x over previous
.LBB0_172:
	s_and_b32 s38, s43, 6
	s_xor_b32 s38, s38, 15
	s_and_b32 s37, s43, 1
	s_sub_i32 s38, s38, s42
	s_or_b32 s39, s43, s42
	s_cmp_eq_u32 s37, 0
	s_cselect_b32 s38, s39, s38
	s_lshl_b32 s44, s38, 8
	v_add_u32_e32 v182, s44, v205
	v_ashrrev_i32_e32 v183, 31, v182
	v_and_b32_e32 v2, 0xfe0, v182
	v_mov_b32_e32 v3, v0
	v_lshlrev_b64 v[2:3], 7, v[2:3]
	v_lshl_add_u64 v[2:3], v[176:177], 0, v[2:3]
	global_load_dwordx4 v[66:69], v[2:3], off
	global_load_dwordx4 v[70:73], v[2:3], off offset:1024
	global_load_dwordx4 v[74:77], v[2:3], off offset:2048
	global_load_dwordx4 v[78:81], v[2:3], off offset:3072
	v_mov_b32_e32 v1, 0x3f80
	v_cndmask_b32_e64 v196, 0, v1, s[16:17]
	v_mov_b32_e32 v197, v0
	v_mov_b32_e32 v198, v0
	v_mov_b32_e32 v199, v0
	v_mov_b32_e32 v162, v0
	v_mov_b32_e32 v163, v0
	v_mov_b32_e32 v164, v0
	v_mov_b32_e32 v165, v0
	s_andn2_b64 vcc, exec, s[30:31]
	s_cbranch_vccnz .LBB0_174
	s_setprio 1

.LBB0_178:
	s_barrier
	s_cmp_lt_u32 s47, 3
	s_cbranch_scc1 .LBB0_180
	s_add_i32 s78, s44, s50
	s_lshl_b64 s[38:39], s[78:79], s41
	s_and_b32 s37, s49, 0xc000
	v_lshl_add_u64 v[208:209], s[38:39], 1, v[180:181]
	s_add_i32 s38, s45, s37
	s_mov_b32 s37, m0
	s_mov_b32 m0, s38
	s_nop 0
	global_load_lds_dwordx4 v[208:209], off
	s_mov_b32 m0, s37
	s_mov_b32 s37, s79
	v_lshl_add_u64 v[208:209], v[208:209], 0, s[36:37]
	s_addk_i32 s38, 0x2000
	s_mov_b32 s37, m0
	s_mov_b32 m0, s38
	s_nop 0
	global_load_lds_dwordx4 v[208:209], off
	s_mov_b32 m0, s37
.LBB0_180:
	s_cmp_gt_i32 s47, s46
	s_cbranch_scc1 .LBB0_188
	s_cmp_lg_u32 s46, s47
	s_cbranch_scc1 .Lfx_body
	v_add_u32_e32 v1, s48, v189
	ds_read_b128 v[126:129], v1 offset:32768
	ds_read_b128 v[106:109], v1 offset:40960
	ds_read_b128 v[98:101], v1 offset:33792
	ds_read_b128 v[102:105], v1 offset:41984
	ds_read_b128 v[86:89], v1 offset:34816
	ds_read_b128 v[94:97], v1 offset:43008
	ds_read_b128 v[82:85], v1 offset:35840
	ds_read_b128 v[90:93], v1 offset:44032
	ds_read_b128 v[34:37], v175
	ds_read_b128 v[38:41], v175 offset:16
	ds_read_b128 v[42:45], v175 offset:64
	ds_read_b128 v[46:49], v175 offset:80
	ds_read_b128 v[50:53], v175 offset:128
	ds_read_b128 v[54:57], v175 offset:144
	ds_read_b128 v[58:61], v175 offset:192
	ds_read_b128 v[62:65], v175 offset:208
	s_waitcnt lgkmcnt(0)
	v_mfma_f32_32x32x16_bf16 v[34:49], v[126:129], v[66:69], v[34:49]
	v_mfma_f32_32x32x16_bf16 v[50:65], v[106:109], v[66:69], v[50:65]
	v_mfma_f32_32x32x16_bf16 v[34:49], v[98:101], v[70:73], v[34:49]
	v_mfma_f32_32x32x16_bf16 v[50:65], v[102:105], v[70:73], v[50:65]
	v_mfma_f32_32x32x16_bf16 v[34:49], v[86:89], v[74:77], v[34:49]
	v_mfma_f32_32x32x16_bf16 v[50:65], v[94:97], v[74:77], v[50:65]
	v_mfma_f32_32x32x16_bf16 v[34:49], v[82:85], v[78:81], v[34:49]
	v_mfma_f32_32x32x16_bf16 v[50:65], v[90:93], v[78:81], v[50:65]
	s_nop 1
	v_add_u32_e32 v1, s50, v166
	v_add_u32_e32 v163, 0xe0, v1
	v_add_u32_e32 v162, 0xc0, v1
	v_cmp_le_i32_e32 vcc, v163, v186
	s_nop 6
	v_cndmask_b32_e32 v50, v239, v50, vcc
	v_cmp_lt_i32_e32 vcc, v162, v186
	s_nop 1
	v_cndmask_b32_e32 v35, v239, v35, vcc
	v_cmp_le_i32_e32 vcc, v162, v186
	v_add_u32_e32 v162, 0xe1, v1
	s_nop 0
	v_cndmask_b32_e32 v34, v239, v34, vcc
	v_cmp_le_i32_e32 vcc, v162, v186
	v_add_u32_e32 v162, 0xc2, v1
	s_nop 0
	v_cndmask_b32_e32 v51, v239, v51, vcc
	v_cmp_le_i32_e32 vcc, v162, v186
	v_add_u32_e32 v162, 0xe2, v1
	s_nop 0
	v_cndmask_b32_e32 v36, v239, v36, vcc
	v_cmp_le_i32_e32 vcc, v162, v186
	v_add_u32_e32 v162, 0xc3, v1
	s_nop 0
	v_cndmask_b32_e32 v52, v239, v52, vcc
	v_cmp_le_i32_e32 vcc, v162, v186
	v_add_u32_e32 v162, 0xe3, v1
	s_nop 0
	v_cndmask_b32_e32 v37, v239, v37, vcc
	v_cmp_le_i32_e32 vcc, v162, v186
	v_add_u32_e32 v162, 0xc4, v1
	s_nop 0
	v_cndmask_b32_e32 v53, v239, v53, vcc
	v_cmp_le_i32_e32 vcc, v162, v186
	v_add_u32_e32 v162, 0xe4, v1
	s_nop 0
	v_cndmask_b32_e32 v38, v239, v38, vcc
	v_cmp_le_i32_e32 vcc, v162, v186
	v_add_u32_e32 v162, 0xc5, v1
	s_nop 0
	v_cndmask_b32_e32 v54, v239, v54, vcc
	v_cmp_le_i32_e32 vcc, v162, v186
	v_add_u32_e32 v162, 0xe5, v1
	s_nop 0
	v_cndmask_b32_e32 v39, v239, v39, vcc
	v_cmp_le_i32_e32 vcc, v162, v186
	v_add_u32_e32 v162, 0xc6, v1
	s_nop 0
	v_cndmask_b32_e32 v55, v239, v55, vcc
	v_cmp_le_i32_e32 vcc, v162, v186
	v_add_u32_e32 v162, 0xe6, v1
	s_nop 0
	v_cndmask_b32_e32 v40, v239, v40, vcc
	v_cmp_le_i32_e32 vcc, v162, v186
	v_add_u32_e32 v162, 0xc7, v1
	s_nop 0
	v_cndmask_b32_e32 v56, v239, v56, vcc
	v_cmp_le_i32_e32 vcc, v162, v186
	v_add_u32_e32 v162, 0xe7, v1
	s_nop 0
	v_cndmask_b32_e32 v41, v239, v41, vcc
	v_cmp_le_i32_e32 vcc, v162, v186
	v_add_u32_e32 v162, 0xd0, v1
	s_nop 0
	v_cndmask_b32_e32 v57, v239, v57, vcc
	v_cmp_le_i32_e32 vcc, v162, v186
	v_add_u32_e32 v162, 0xf0, v1
	s_nop 0
	v_cndmask_b32_e32 v42, v239, v42, vcc
	v_cmp_le_i32_e32 vcc, v162, v186
	v_add_u32_e32 v162, 0xd1, v1
	s_nop 0
	v_cndmask_b32_e32 v58, v239, v58, vcc
	v_cmp_le_i32_e32 vcc, v162, v186
	v_add_u32_e32 v162, 0xf1, v1
	s_nop 0
	v_cndmask_b32_e32 v43, v239, v43, vcc
	v_cmp_le_i32_e32 vcc, v162, v186
	v_add_u32_e32 v162, 0xd2, v1
	s_nop 0
	v_cndmask_b32_e32 v59, v239, v59, vcc
	v_cmp_le_i32_e32 vcc, v162, v186
	v_add_u32_e32 v162, 0xf2, v1
	s_nop 0
	v_cndmask_b32_e32 v44, v239, v44, vcc
	v_cmp_le_i32_e32 vcc, v162, v186
	v_add_u32_e32 v162, 0xd3, v1
	s_nop 0
	v_cndmask_b32_e32 v60, v239, v60, vcc
	v_cmp_le_i32_e32 vcc, v162, v186
	v_add_u32_e32 v162, 0xf3, v1
	s_nop 0
	v_cndmask_b32_e32 v45, v239, v45, vcc
	v_cmp_le_i32_e32 vcc, v162, v186
	v_add_u32_e32 v162, 0xd4, v1
	s_nop 0
	v_cndmask_b32_e32 v61, v239, v61, vcc
	v_cmp_le_i32_e32 vcc, v162, v186
	v_add_u32_e32 v162, 0xf4, v1
	s_nop 0
	v_cndmask_b32_e32 v46, v239, v46, vcc
	v_cmp_le_i32_e32 vcc, v162, v186
	v_add_u32_e32 v162, 0xd5, v1
	s_nop 0
	v_cndmask_b32_e32 v62, v239, v62, vcc
	v_cmp_le_i32_e32 vcc, v162, v186
	v_add_u32_e32 v162, 0xf5, v1
	s_nop 0
	v_cndmask_b32_e32 v47, v239, v47, vcc
	v_cmp_le_i32_e32 vcc, v162, v186
	v_add_u32_e32 v162, 0xd6, v1
	s_nop 0
	v_cndmask_b32_e32 v63, v239, v63, vcc
	v_cmp_le_i32_e32 vcc, v162, v186
	v_add_u32_e32 v162, 0xf6, v1
	s_nop 0
	v_cndmask_b32_e32 v48, v239, v48, vcc
	v_cmp_le_i32_e32 vcc, v162, v186
	v_add_u32_e32 v162, 0xd7, v1
	v_add_u32_e32 v1, 0xf7, v1
	v_cndmask_b32_e32 v64, v239, v64, vcc
	v_cmp_le_i32_e32 vcc, v162, v186
	s_nop 1
	v_cndmask_b32_e32 v49, v239, v49, vcc
	v_cmp_le_i32_e32 vcc, v1, v186
	s_nop 1
	v_cndmask_b32_e32 v65, v239, v65, vcc
	v_mov_b32_e32 v163, v0
	v_max3_f32 v1, v34, v35, v36
	v_max3_f32 v208, v50, v51, v52
	v_max3_f32 v1, v1, v37, v38
	v_max3_f32 v1, v1, v39, v40
	v_max3_f32 v1, v1, v41, v42
	v_max3_f32 v1, v1, v43, v44
	v_max3_f32 v1, v1, v45, v46
	v_max3_f32 v1, v1, v47, v48
	v_max3_f32 v208, v208, v53, v54
	v_max3_f32 v208, v208, v55, v56
	v_max3_f32 v208, v208, v57, v58
	v_max3_f32 v208, v208, v59, v60
	v_max3_f32 v208, v208, v61, v62
	v_max3_f32 v208, v208, v63, v64
	v_max3_f32 v208, v208, v65, v49
	v_max_f32_e32 v1, v1, v208
	ds_bpermute_b32 v209, v203, v1
	s_waitcnt lgkmcnt(0)
	v_max_f32_e32 v1, v1, v209
	v_cvt_pk_bf16_f32 v209, v1, v1
	v_lshlrev_b32_e32 v200, 16, v209
	v_xor_b32_e32 v209, 0x8000, v209
	v_and_b32_e32 v209, 0xffff, v209
	v_cndmask_b32_e64 v162, 0, v209, s[16:17]
	v_sub_f32_e32 v34, v34, v200
	v_sub_f32_e32 v35, v35, v200
	v_sub_f32_e32 v36, v36, v200
	v_sub_f32_e32 v37, v37, v200
	v_sub_f32_e32 v38, v38, v200
	v_sub_f32_e32 v39, v39, v200
	v_sub_f32_e32 v40, v40, v200
	v_sub_f32_e32 v41, v41, v200
	v_sub_f32_e32 v42, v42, v200
	v_sub_f32_e32 v43, v43, v200
	v_sub_f32_e32 v44, v44, v200
	v_sub_f32_e32 v45, v45, v200
	v_sub_f32_e32 v46, v46, v200
	v_sub_f32_e32 v47, v47, v200
	v_sub_f32_e32 v48, v48, v200
	v_sub_f32_e32 v49, v49, v200
	v_sub_f32_e32 v50, v50, v200
	v_sub_f32_e32 v51, v51, v200
	v_sub_f32_e32 v52, v52, v200
	v_sub_f32_e32 v53, v53, v200
	v_sub_f32_e32 v54, v54, v200
	v_sub_f32_e32 v55, v55, v200
	v_sub_f32_e32 v56, v56, v200
	v_sub_f32_e32 v57, v57, v200
	v_sub_f32_e32 v58, v58, v200
	v_sub_f32_e32 v59, v59, v200
	v_sub_f32_e32 v60, v60, v200
	v_sub_f32_e32 v61, v61, v200
	v_sub_f32_e32 v62, v62, v200
	v_sub_f32_e32 v63, v63, v200
	v_sub_f32_e32 v64, v64, v200
	v_sub_f32_e32 v65, v65, v200
.Lfx_body:
	s_add_i32 s37, s49, 0x18000
	s_and_b32 s37, s37, 0xc000
	v_add_u32_e32 v1, s37, v189
	ds_read_b128 v[126:129], v1 offset:32768
	ds_read_b128 v[106:109], v1 offset:40960
	ds_read_b128 v[98:101], v1 offset:33792
	ds_read_b128 v[102:105], v1 offset:41984
	ds_read_b128 v[86:89], v1 offset:34816
	ds_read_b128 v[94:97], v1 offset:43008
	ds_read_b128 v[82:85], v1 offset:35840
	ds_read_b128 v[90:93], v1 offset:44032
	s_add_i32 s37, s49, 0xc000
	s_and_b32 s37, s37, 0xc000
	v_add_u32_e32 v194, s37, v189
	v_mfma_f32_32x32x16_bf16 v[18:33], v[158:161], v[122:125], v[18:33]
	v_exp_f32_e32 v208, v34
	v_exp_f32_e32 v209, v35
	v_exp_f32_e32 v210, v36
	v_exp_f32_e32 v211, v37
	ds_read_b128 v[158:161], v194 offset:36864
	v_mfma_f32_32x32x16_bf16 v[18:33], v[154:157], v[118:121], v[18:33]
	v_exp_f32_e32 v212, v38
	v_exp_f32_e32 v213, v39
	v_exp_f32_e32 v214, v40
	v_exp_f32_e32 v215, v41
	ds_read_b128 v[154:157], v194 offset:37888
	v_mfma_f32_32x32x16_bf16 v[2:17], v[142:145], v[122:125], v[2:17]
	v_exp_f32_e32 v216, v42
	v_exp_f32_e32 v217, v43
	v_exp_f32_e32 v218, v44
	v_exp_f32_e32 v219, v45
	ds_read_b128 v[142:145], v194 offset:38912
	v_mfma_f32_32x32x16_bf16 v[18:33], v[150:153], v[114:117], v[18:33]
	v_exp_f32_e32 v220, v46
	v_exp_f32_e32 v221, v47
	v_exp_f32_e32 v222, v48
	v_exp_f32_e32 v223, v49
	ds_read_b128 v[150:153], v194 offset:45056
	v_mfma_f32_32x32x16_bf16 v[2:17], v[138:141], v[118:121], v[2:17]
	v_exp_f32_e32 v224, v50
	v_exp_f32_e32 v225, v51
	v_exp_f32_e32 v226, v52
	v_exp_f32_e32 v227, v53
	ds_read_b128 v[138:141], v194 offset:39936
	v_mfma_f32_32x32x16_bf16 v[18:33], v[146:149], v[110:113], v[18:33]
	v_exp_f32_e32 v228, v54
	v_exp_f32_e32 v229, v55
	v_exp_f32_e32 v230, v56
	v_exp_f32_e32 v231, v57
	ds_read_b128 v[146:149], v194 offset:46080
	v_mfma_f32_32x32x16_bf16 v[2:17], v[134:137], v[114:117], v[2:17]
	v_exp_f32_e32 v244, v58
	v_exp_f32_e32 v245, v59
	v_exp_f32_e32 v246, v60
	v_exp_f32_e32 v247, v61
	ds_read_b128 v[134:137], v194 offset:47104
	v_mfma_f32_32x32x16_bf16 v[2:17], v[130:133], v[110:113], v[2:17]
	v_exp_f32_e32 v248, v62
	v_exp_f32_e32 v249, v63
	v_exp_f32_e32 v250, v64
	v_exp_f32_e32 v251, v65
	ds_read_b128 v[130:133], v194 offset:48128
	v_add_u32_e32 v195, 0xffffff00, v175
	v_max_i32_e32 v195, v195, v0
	ds_read_b128 v[34:37], v195
	ds_read_b128 v[38:41], v195 offset:16
	ds_read_b128 v[42:45], v195 offset:64
	ds_read_b128 v[46:49], v195 offset:80
	ds_read_b128 v[50:53], v195 offset:128
	ds_read_b128 v[54:57], v195 offset:144
	ds_read_b128 v[58:61], v195 offset:192
	ds_read_b128 v[62:65], v195 offset:208
	v_add_f32_e32 v110, v208, v209
	v_add_f32_e32 v111, v210, v211
	v_add_f32_e32 v112, v212, v213
	v_add_f32_e32 v113, v214, v215
	s_waitcnt lgkmcnt(4)
	v_mfma_f32_32x32x16_bf16 v[34:49], v[126:129], v[66:69], v[34:49]
	v_add_f32_e32 v110, v216, v110
	v_add_f32_e32 v111, v217, v111
	v_add_f32_e32 v112, v218, v112
	s_waitcnt lgkmcnt(0)
	v_mfma_f32_32x32x16_bf16 v[50:65], v[106:109], v[66:69], v[50:65]
	v_add_f32_e32 v113, v219, v113
	v_add_f32_e32 v110, v220, v110
	v_add_f32_e32 v111, v221, v111
	v_mfma_f32_32x32x16_bf16 v[34:49], v[98:101], v[70:73], v[34:49]
	v_add_f32_e32 v112, v222, v112
	v_add_f32_e32 v113, v223, v113
	v_add_f32_e32 v110, v224, v110
	v_mfma_f32_32x32x16_bf16 v[50:65], v[102:105], v[70:73], v[50:65]
	v_add_f32_e32 v111, v225, v111
	v_add_f32_e32 v112, v226, v112
	v_add_f32_e32 v113, v227, v113
	v_mfma_f32_32x32x16_bf16 v[34:49], v[86:89], v[74:77], v[34:49]
	v_add_f32_e32 v110, v228, v110
	v_add_f32_e32 v111, v229, v111
	v_add_f32_e32 v112, v230, v112
	v_mfma_f32_32x32x16_bf16 v[50:65], v[94:97], v[74:77], v[50:65]
	v_add_f32_e32 v113, v231, v113
	v_add_f32_e32 v110, v244, v110
	v_add_f32_e32 v111, v245, v111
	v_mfma_f32_32x32x16_bf16 v[34:49], v[82:85], v[78:81], v[34:49]
	v_add_f32_e32 v112, v246, v112
	v_add_f32_e32 v113, v247, v113
	v_add_f32_e32 v110, v248, v110
	v_mfma_f32_32x32x16_bf16 v[50:65], v[90:93], v[78:81], v[50:65]
	v_add_f32_e32 v111, v249, v111
	v_add_f32_e32 v112, v250, v112
	v_add_f32_e32 v113, v251, v113
	v_mfma_f32_32x32x16_bf16 v[34:49], v[196:199], v[162:165], v[34:49]
	v_mfma_f32_32x32x16_bf16 v[50:65], v[196:199], v[162:165], v[50:65]
	v_add_f32_e32 v110, v110, v111
	v_add_f32_e32 v112, v112, v113
	v_add_f32_e32 v114, v110, v112
	v_cmp_lt_f32_e32 vcc, 0x49800000, v114
	s_cbranch_vccnz .Lfx_rare
.Lfx_rare_back:
	v_add_f32_e32 v206, v206, v114
	v_cvt_pk_bf16_f32 v122, v208, v209
	v_cvt_pk_bf16_f32 v123, v210, v211
	v_cvt_pk_bf16_f32 v124, v212, v213
	v_cvt_pk_bf16_f32 v125, v214, v215
	v_cvt_pk_bf16_f32 v118, v216, v217
	v_cvt_pk_bf16_f32 v119, v218, v219
	v_cvt_pk_bf16_f32 v120, v220, v221
	v_cvt_pk_bf16_f32 v121, v222, v223
	v_cvt_pk_bf16_f32 v114, v224, v225
	v_cvt_pk_bf16_f32 v115, v226, v227
	v_cvt_pk_bf16_f32 v116, v228, v229
	v_cvt_pk_bf16_f32 v117, v230, v231
	v_cvt_pk_bf16_f32 v110, v244, v245
	v_cvt_pk_bf16_f32 v111, v246, v247
	v_cvt_pk_bf16_f32 v112, v248, v249
	v_cvt_pk_bf16_f32 v113, v250, v251
	s_branch .LBB0_189
.Lfx_rare:
	s_nop 7
	s_nop 7
	ds_bpermute_b32 v115, v203, v114
	s_waitcnt lgkmcnt(0)
	v_max_f32_e32 v115, v115, v114
	v_max_f32_e32 v115, 1.0, v115
	v_log_f32_e32 v115, v115
	s_nop 0
	v_floor_f32_e32 v115, v115
	v_add_f32_e32 v116, v200, v115
	v_cvt_pk_bf16_f32 v117, v116, v116
	v_lshlrev_b32_e32 v116, 16, v117
	v_sub_f32_e32 v115, v116, v200
	v_mov_b32_e32 v200, v116
	v_xor_b32_e32 v117, 0x8000, v117
	v_and_b32_e32 v117, 0xffff, v117
	v_cndmask_b32_e64 v162, 0, v117, s[16:17]
	v_exp_f32_e64 v116, -v115
	s_nop 0
	v_pk_mul_f32 v[32:33], v[32:33], v[116:117] op_sel_hi:[1,0]
	v_pk_mul_f32 v[30:31], v[30:31], v[116:117] op_sel_hi:[1,0]
	v_pk_mul_f32 v[28:29], v[28:29], v[116:117] op_sel_hi:[1,0]
	v_pk_mul_f32 v[26:27], v[26:27], v[116:117] op_sel_hi:[1,0]
	v_pk_mul_f32 v[24:25], v[24:25], v[116:117] op_sel_hi:[1,0]
	v_pk_mul_f32 v[22:23], v[22:23], v[116:117] op_sel_hi:[1,0]
	v_pk_mul_f32 v[20:21], v[20:21], v[116:117] op_sel_hi:[1,0]
	v_pk_mul_f32 v[18:19], v[18:19], v[116:117] op_sel_hi:[1,0]
	v_pk_mul_f32 v[16:17], v[16:17], v[116:117] op_sel_hi:[1,0]
	v_pk_mul_f32 v[14:15], v[14:15], v[116:117] op_sel_hi:[1,0]
	v_pk_mul_f32 v[12:13], v[12:13], v[116:117] op_sel_hi:[1,0]
	v_pk_mul_f32 v[10:11], v[10:11], v[116:117] op_sel_hi:[1,0]
	v_pk_mul_f32 v[8:9], v[8:9], v[116:117] op_sel_hi:[1,0]
	v_pk_mul_f32 v[6:7], v[6:7], v[116:117] op_sel_hi:[1,0]
	v_pk_mul_f32 v[4:5], v[4:5], v[116:117] op_sel_hi:[1,0]
	v_pk_mul_f32 v[2:3], v[2:3], v[116:117] op_sel_hi:[1,0]
	v_mul_f32_e32 v208, v208, v116
	v_mul_f32_e32 v209, v209, v116
	v_mul_f32_e32 v210, v210, v116
	v_mul_f32_e32 v211, v211, v116
	v_mul_f32_e32 v212, v212, v116
	v_mul_f32_e32 v213, v213, v116
	v_mul_f32_e32 v214, v214, v116
	v_mul_f32_e32 v215, v215, v116
	v_mul_f32_e32 v216, v216, v116
	v_mul_f32_e32 v217, v217, v116
	v_mul_f32_e32 v218, v218, v116
	v_mul_f32_e32 v219, v219, v116
	v_mul_f32_e32 v220, v220, v116
	v_mul_f32_e32 v221, v221, v116
	v_mul_f32_e32 v222, v222, v116
	v_mul_f32_e32 v223, v223, v116
	v_mul_f32_e32 v224, v224, v116
	v_mul_f32_e32 v225, v225, v116
	v_mul_f32_e32 v226, v226, v116
	v_mul_f32_e32 v227, v227, v116
	v_mul_f32_e32 v228, v228, v116
	v_mul_f32_e32 v229, v229, v116
	v_mul_f32_e32 v230, v230, v116
	v_mul_f32_e32 v231, v231, v116
	v_mul_f32_e32 v244, v244, v116
	v_mul_f32_e32 v245, v245, v116
	v_mul_f32_e32 v246, v246, v116
	v_mul_f32_e32 v247, v247, v116
	v_mul_f32_e32 v248, v248, v116
	v_mul_f32_e32 v249, v249, v116
	v_mul_f32_e32 v250, v250, v116
	v_mul_f32_e32 v251, v251, v116
	v_mul_f32_e32 v114, v114, v116
	v_mul_f32_e32 v206, v206, v116
	v_sub_f32_e32 v34, v34, v115
	v_sub_f32_e32 v35, v35, v115
	v_sub_f32_e32 v36, v36, v115
	v_sub_f32_e32 v37, v37, v115
	v_sub_f32_e32 v38, v38, v115
	v_sub_f32_e32 v39, v39, v115
	v_sub_f32_e32 v40, v40, v115
	v_sub_f32_e32 v41, v41, v115
	v_sub_f32_e32 v42, v42, v115
	v_sub_f32_e32 v43, v43, v115
	v_sub_f32_e32 v44, v44, v115
	v_sub_f32_e32 v45, v45, v115
	v_sub_f32_e32 v46, v46, v115
	v_sub_f32_e32 v47, v47, v115
	v_sub_f32_e32 v48, v48, v115
	v_sub_f32_e32 v49, v49, v115
	v_sub_f32_e32 v50, v50, v115
	v_sub_f32_e32 v51, v51, v115
	v_sub_f32_e32 v52, v52, v115
	v_sub_f32_e32 v53, v53, v115
	v_sub_f32_e32 v54, v54, v115
	v_sub_f32_e32 v55, v55, v115
	v_sub_f32_e32 v56, v56, v115
	v_sub_f32_e32 v57, v57, v115
	v_sub_f32_e32 v58, v58, v115
	v_sub_f32_e32 v59, v59, v115
	v_sub_f32_e32 v60, v60, v115
	v_sub_f32_e32 v61, v61, v115
	v_sub_f32_e32 v62, v62, v115
	v_sub_f32_e32 v63, v63, v115
	v_sub_f32_e32 v64, v64, v115
	v_sub_f32_e32 v65, v65, v115
	s_branch .Lfx_rare_back
